# P6 swiglu epilogue: hoist the 8 rs loads, no store drains; P8: preload the 16 g chunks, no per-step vmcnt(0) drain
# speedup vs baseline: 1.0157x; 1.0157x over previous
; __device__ __forceinline__ u32x4 pack8f(const f32x4 a, const f32x4 b) { u32x4 w; w.x = cvt_pk_bf16(a[0], a[1]); w.y = cvt_pk_bf16(a[2], a[3]); w.z = cvt_pk_bf16(b[0], b[1]); w.w = cvt_pk_bf16(b[2], b[3]); return w; }
;     __device__ __forceinline__ void operator()(const f32x4 (&acc)[2][2][4][2], const Unit& u, int wr, int wc, int fr, int fq) const {
;     ...
;                 const int row = u.pm * BM + ai * HALF + wr * 64 + m * 16 + fr; const float rr = rs[row];
;                 f32x4 r0, r1;
; #pragma unroll
;                 for (int e = 0; e < 4; ++e) {
;                     const float g0 = acc[ai][0][m][0][e] * rr, g1 = acc[ai][0][m][1][e] * rr;
;                     r0[e] = g0 * __builtin_amdgcn_rcpf(1.f + __builtin_amdgcn_exp2f(-1.4426950408889634f * g0)) * (acc[ai][1][m][0][e] * rr);
;                     r1[e] = g1 * __builtin_amdgcn_rcpf(1.f + __builtin_amdgcn_exp2f(-1.4426950408889634f * g1)) * (acc[ai][1][m][1][e] * rr);
;                 }
;                 *(u32x4*)(O + (size_t)row * ldc + col0) = pack8f(r0, r1);
.LBB0_884:
	v_lshl_add_u32 v146, s42, 8, v149
	v_ashrrev_i32_e32 v147, 31, v146
	v_lshl_add_u64 v[156:157], v[146:147], 2, s[10:11]
	global_load_dword v172, v[156:157], off
	global_load_dword v174, v[156:157], off offset:64
	global_load_dword v176, v[156:157], off offset:128
	global_load_dword v178, v[156:157], off offset:192
	global_load_dword v180, v[156:157], off offset:512
	global_load_dword v182, v[156:157], off offset:576
	global_load_dword v184, v[156:157], off offset:640
	global_load_dword v186, v[156:157], off offset:704
	v_lshl_or_b32 v158, s69, 7, v151
	v_mov_b32_e32 v160, v126
	v_mov_b32_e32 v161, v122
	v_mov_b32_e32 v163, v114
	v_mov_b32_e32 v122, v127
	v_mov_b32_e32 v114, v119
	v_mov_b32_e32 v126, v128
	v_mov_b32_e32 v127, v124
	v_mov_b32_e32 v165, v116
	v_mov_b32_e32 v116, v121
	v_or_b32_e32 v166, 16, v146
	v_mov_b32_e32 v162, v118
	v_mov_b32_e32 v164, v120
	v_mov_b32_e32 v124, v129
	v_ashrrev_i32_e32 v159, 31, v158
	v_ashrrev_i32_e32 v167, 31, v166
	v_lshlrev_b64 v[120:121], 1, v[158:159]
	v_lshl_add_u64 v[158:159], v[166:167], 2, s[10:11]
	v_mov_b64_e32 v[118:119], s[8:9]
	v_mad_i64_i32 v[128:129], s[44:45], v146, s68, v[118:119]
	v_lshl_add_u64 v[128:129], v[128:129], 0, v[120:121]
	s_andn2_b64 vcc, exec, s[2:3]
	s_mov_b64 s[2:3], -1
	s_waitcnt vmcnt(0)
	v_mov_b32_e32 v156, v172
	v_pk_mul_f32 v[122:123], v[122:123], v[156:157] op_sel_hi:[1,0]
	v_pk_mul_f32 v[114:115], v[114:115], v[156:157] op_sel_hi:[1,0]
	v_pk_mul_f32 v[126:127], v[126:127], v[156:157] op_sel_hi:[1,0]
	v_pk_mul_f32 v[116:117], v[116:117], v[156:157] op_sel_hi:[1,0]
	v_pk_mul_f32 v[160:161], v[160:161], v[156:157] op_sel_hi:[1,0]
	v_pk_mul_f32 v[162:163], v[162:163], v[156:157] op_sel_hi:[1,0]
	v_pk_mul_f32 v[164:165], v[164:165], v[156:157] op_sel_hi:[1,0]
	v_pk_mul_f32 v[124:125], v[124:125], v[156:157] op_sel_hi:[1,0]
	v_mul_f32_e32 v156, 0xbfb8aa3b, v123
	v_mul_f32_e32 v157, 0xbfb8aa3b, v115
	v_mul_f32_e32 v167, 0xbfb8aa3b, v127
	v_mul_f32_e32 v170, 0xbfb8aa3b, v117
	v_mul_f32_e32 v147, 0xbfb8aa3b, v161
	v_mul_f32_e32 v155, 0xbfb8aa3b, v163
	v_mul_f32_e32 v168, 0xbfb8aa3b, v165
	v_mul_f32_e32 v169, 0xbfb8aa3b, v125
	v_exp_f32_e32 v156, v156
	v_exp_f32_e32 v157, v157
	v_exp_f32_e32 v167, v167
	v_exp_f32_e32 v170, v170
	v_exp_f32_e32 v147, v147
	v_exp_f32_e32 v155, v155
	v_exp_f32_e32 v168, v168
	v_exp_f32_e32 v169, v169
	v_add_f32_e32 v156, 1.0, v156
	v_add_f32_e32 v157, 1.0, v157
	v_add_f32_e32 v167, 1.0, v167
	v_add_f32_e32 v170, 1.0, v170
	v_add_f32_e32 v147, 1.0, v147
	v_add_f32_e32 v155, 1.0, v155
	v_add_f32_e32 v168, 1.0, v168
	v_add_f32_e32 v169, 1.0, v169
	v_rcp_f32_e32 v156, v156
	v_rcp_f32_e32 v157, v157
	v_rcp_f32_e32 v167, v167
	v_rcp_f32_e32 v170, v170
	v_rcp_f32_e32 v147, v147
	v_rcp_f32_e32 v155, v155
	v_rcp_f32_e32 v168, v168
	v_rcp_f32_e32 v169, v169
	v_mul_f32_e32 v123, v123, v156
	v_mul_f32_e32 v115, v115, v157
	v_mul_f32_e32 v127, v127, v167
	v_mul_f32_e32 v117, v117, v170
	v_mul_f32_e32 v147, v161, v147
	v_mul_f32_e32 v155, v163, v155
	v_mul_f32_e32 v156, v165, v168
	v_mul_f32_e32 v125, v125, v169
	v_mul_f32_e32 v122, v122, v123
	v_mul_f32_e32 v123, v114, v115
	v_mul_f32_e32 v115, v126, v127
	v_mul_f32_e32 v117, v116, v117
	v_mul_f32_e32 v147, v160, v147
	v_mul_f32_e32 v155, v162, v155
	v_mul_f32_e32 v126, v164, v156
	v_mul_f32_e32 v124, v124, v125
	v_cvt_pk_bf16_f32 v114, v147, v122
	v_cvt_pk_bf16_f32 v115, v115, v124
	v_cvt_pk_bf16_f32 v116, v155, v123
	v_cvt_pk_bf16_f32 v117, v126, v117
	global_store_dwordx4 v[128:129], v[114:117], off
	s_nop 1
	v_mov_b32_e32 v122, v102
	v_mov_b32_e32 v117, v106
	v_mov_b32_e32 v123, v98
	v_mov_b32_e32 v106, v111
	v_mov_b32_e32 v98, v103
	v_mov_b32_e32 v102, v112
	v_mov_b32_e32 v103, v108
	v_mov_b32_e32 v111, v100
	v_mov_b32_e32 v100, v105
	v_mov_b32_e32 v116, v110
	v_mov_b32_e32 v110, v104
	v_mov_b32_e32 v108, v113
	v_or_b32_e32 v104, 32, v146
	v_ashrrev_i32_e32 v105, 31, v104
	v_lshl_add_u64 v[124:125], v[104:105], 2, s[10:11]
	v_mad_i64_i32 v[112:113], s[44:45], v166, s68, v[118:119]
	v_lshl_add_u64 v[112:113], v[112:113], 0, v[120:121]
	v_mov_b32_e32 v114, v174
	v_pk_mul_f32 v[106:107], v[106:107], v[114:115] op_sel_hi:[1,0]
	v_pk_mul_f32 v[98:99], v[98:99], v[114:115] op_sel_hi:[1,0]
	v_pk_mul_f32 v[102:103], v[102:103], v[114:115] op_sel_hi:[1,0]
	v_pk_mul_f32 v[100:101], v[100:101], v[114:115] op_sel_hi:[1,0]
	v_pk_mul_f32 v[116:117], v[116:117], v[114:115] op_sel_hi:[1,0]
	v_pk_mul_f32 v[122:123], v[122:123], v[114:115] op_sel_hi:[1,0]
	v_pk_mul_f32 v[110:111], v[110:111], v[114:115] op_sel_hi:[1,0]
	v_pk_mul_f32 v[108:109], v[108:109], v[114:115] op_sel_hi:[1,0]
	v_mul_f32_e32 v115, 0xbfb8aa3b, v107
	v_mul_f32_e32 v126, 0xbfb8aa3b, v99
	v_mul_f32_e32 v127, 0xbfb8aa3b, v103
	v_mul_f32_e32 v147, 0xbfb8aa3b, v101
	v_mul_f32_e32 v105, 0xbfb8aa3b, v117
	v_mul_f32_e32 v114, 0xbfb8aa3b, v123
	v_mul_f32_e32 v128, 0xbfb8aa3b, v111
	v_mul_f32_e32 v129, 0xbfb8aa3b, v109
	v_exp_f32_e32 v115, v115
	v_exp_f32_e32 v126, v126
	v_exp_f32_e32 v127, v127
	v_exp_f32_e32 v147, v147
	v_exp_f32_e32 v105, v105
	v_exp_f32_e32 v114, v114
	v_exp_f32_e32 v128, v128
	v_exp_f32_e32 v129, v129
	v_add_f32_e32 v115, 1.0, v115
	v_add_f32_e32 v126, 1.0, v126
	v_add_f32_e32 v127, 1.0, v127
	v_add_f32_e32 v147, 1.0, v147
	v_add_f32_e32 v105, 1.0, v105
	v_add_f32_e32 v114, 1.0, v114
	v_add_f32_e32 v128, 1.0, v128
	v_add_f32_e32 v129, 1.0, v129
	v_rcp_f32_e32 v115, v115
	v_rcp_f32_e32 v126, v126
	v_rcp_f32_e32 v127, v127
	v_rcp_f32_e32 v147, v147
	v_rcp_f32_e32 v105, v105
	v_rcp_f32_e32 v114, v114
	v_rcp_f32_e32 v128, v128
	v_rcp_f32_e32 v129, v129
	v_mul_f32_e32 v107, v107, v115
	v_mul_f32_e32 v99, v99, v126
; __device__ __forceinline__ u32x4 pack8f(const f32x4 a, const f32x4 b) { u32x4 w; w.x = cvt_pk_bf16(a[0], a[1]); w.y = cvt_pk_bf16(a[2], a[3]); w.z = cvt_pk_bf16(b[0], b[1]); w.w = cvt_pk_bf16(b[2], b[3]); return w; }
;     __device__ __forceinline__ void operator()(const f32x4 (&acc)[2][2][4][2], const Unit& u, int wr, int wc, int fr, int fq) const {
;     ...
;                 const int row = u.pm * BM + ai * HALF + wr * 64 + m * 16 + fr; const float rr = rs[row];
;                 f32x4 r0, r1;
; #pragma unroll
;                 for (int e = 0; e < 4; ++e) {
;                     const float g0 = acc[ai][0][m][0][e] * rr, g1 = acc[ai][0][m][1][e] * rr;
;                     r0[e] = g0 * __builtin_amdgcn_rcpf(1.f + __builtin_amdgcn_exp2f(-1.4426950408889634f * g0)) * (acc[ai][1][m][0][e] * rr);
;                     r1[e] = g1 * __builtin_amdgcn_rcpf(1.f + __builtin_amdgcn_exp2f(-1.4426950408889634f * g1)) * (acc[ai][1][m][1][e] * rr);
;                 }
;                 *(u32x4*)(O + (size_t)row * ldc + col0) = pack8f(r0, r1);
	v_mul_f32_e32 v103, v103, v127
	v_mul_f32_e32 v101, v101, v147
	v_mul_f32_e32 v105, v117, v105
	v_mul_f32_e32 v114, v123, v114
	v_mul_f32_e32 v111, v111, v128
	v_mul_f32_e32 v109, v109, v129
	v_mul_f32_e32 v106, v106, v107
	v_mul_f32_e32 v107, v98, v99
	v_mul_f32_e32 v99, v102, v103
	v_mul_f32_e32 v101, v100, v101
	v_mul_f32_e32 v105, v116, v105
	v_mul_f32_e32 v114, v122, v114
	v_mul_f32_e32 v102, v110, v111
	v_mul_f32_e32 v103, v108, v109
	v_cvt_pk_bf16_f32 v98, v105, v106
	v_cvt_pk_bf16_f32 v99, v99, v103
	v_cvt_pk_bf16_f32 v100, v114, v107
	v_cvt_pk_bf16_f32 v101, v102, v101
	global_store_dwordx4 v[112:113], v[98:101], off
	s_nop 1
	v_mov_b32_e32 v102, v86
	v_mov_b32_e32 v101, v90
	v_mov_b32_e32 v103, v82
	v_mov_b32_e32 v90, v95
	v_mov_b32_e32 v82, v87
	v_mov_b32_e32 v86, v96
	v_mov_b32_e32 v87, v92
	v_mov_b32_e32 v95, v84
	v_mov_b32_e32 v84, v89
	v_mov_b32_e32 v100, v94
	v_mov_b32_e32 v94, v88
	v_mov_b32_e32 v92, v97
	v_or_b32_e32 v88, 48, v146
	v_ashrrev_i32_e32 v89, 31, v88
	v_mad_i64_i32 v[96:97], s[44:45], v104, s68, v[118:119]
	v_lshl_add_u64 v[104:105], v[88:89], 2, s[10:11]
	v_lshl_add_u64 v[96:97], v[96:97], 0, v[120:121]
	v_mov_b32_e32 v98, v176
	v_pk_mul_f32 v[90:91], v[90:91], v[98:99] op_sel_hi:[1,0]
	v_pk_mul_f32 v[82:83], v[82:83], v[98:99] op_sel_hi:[1,0]
	v_pk_mul_f32 v[86:87], v[86:87], v[98:99] op_sel_hi:[1,0]
	v_pk_mul_f32 v[84:85], v[84:85], v[98:99] op_sel_hi:[1,0]
	v_pk_mul_f32 v[100:101], v[100:101], v[98:99] op_sel_hi:[1,0]
	v_pk_mul_f32 v[102:103], v[102:103], v[98:99] op_sel_hi:[1,0]
	v_pk_mul_f32 v[94:95], v[94:95], v[98:99] op_sel_hi:[1,0]
	v_pk_mul_f32 v[92:93], v[92:93], v[98:99] op_sel_hi:[1,0]
	v_mul_f32_e32 v99, 0xbfb8aa3b, v91
	v_mul_f32_e32 v106, 0xbfb8aa3b, v83
	v_mul_f32_e32 v107, 0xbfb8aa3b, v87
	v_mul_f32_e32 v110, 0xbfb8aa3b, v85
	v_mul_f32_e32 v89, 0xbfb8aa3b, v101
	v_mul_f32_e32 v98, 0xbfb8aa3b, v103
	v_mul_f32_e32 v108, 0xbfb8aa3b, v95
	v_mul_f32_e32 v109, 0xbfb8aa3b, v93
	v_exp_f32_e32 v99, v99
	v_exp_f32_e32 v106, v106
	v_exp_f32_e32 v107, v107
	v_exp_f32_e32 v110, v110
	v_exp_f32_e32 v89, v89
	v_exp_f32_e32 v98, v98
	v_exp_f32_e32 v108, v108
	v_exp_f32_e32 v109, v109
	v_add_f32_e32 v99, 1.0, v99
	v_add_f32_e32 v106, 1.0, v106
	v_add_f32_e32 v107, 1.0, v107
	v_add_f32_e32 v110, 1.0, v110
	v_add_f32_e32 v89, 1.0, v89
	v_add_f32_e32 v98, 1.0, v98
	v_add_f32_e32 v108, 1.0, v108
	v_add_f32_e32 v109, 1.0, v109
	v_rcp_f32_e32 v99, v99
	v_rcp_f32_e32 v106, v106
	v_rcp_f32_e32 v107, v107
	v_rcp_f32_e32 v110, v110
	v_rcp_f32_e32 v89, v89
	v_rcp_f32_e32 v98, v98
	v_rcp_f32_e32 v108, v108
	v_rcp_f32_e32 v109, v109
	v_mul_f32_e32 v91, v91, v99
	v_mul_f32_e32 v83, v83, v106
	v_mul_f32_e32 v87, v87, v107
	v_mul_f32_e32 v85, v85, v110
	v_mul_f32_e32 v89, v101, v89
	v_mul_f32_e32 v98, v103, v98
	v_mul_f32_e32 v95, v95, v108
	v_mul_f32_e32 v93, v93, v109
	v_mul_f32_e32 v90, v90, v91
	v_mul_f32_e32 v91, v82, v83
	v_mul_f32_e32 v83, v86, v87
	v_mul_f32_e32 v85, v84, v85
	v_mul_f32_e32 v89, v100, v89
	v_mul_f32_e32 v98, v102, v98
	v_mul_f32_e32 v86, v94, v95
	v_mul_f32_e32 v87, v92, v93
	v_cvt_pk_bf16_f32 v82, v89, v90
	v_cvt_pk_bf16_f32 v83, v83, v87
	v_cvt_pk_bf16_f32 v84, v98, v91
	v_cvt_pk_bf16_f32 v85, v86, v85
	global_store_dwordx4 v[96:97], v[82:85], off
	s_nop 1
	v_mov_b32_e32 v86, v70
	v_mov_b32_e32 v85, v74
	v_mov_b32_e32 v87, v66
	v_mov_b32_e32 v74, v79
	v_mov_b32_e32 v66, v71
	v_mov_b32_e32 v70, v80
	v_mov_b32_e32 v71, v76
	v_mov_b32_e32 v79, v68
	v_mov_b32_e32 v68, v73
	v_mov_b32_e32 v84, v78
	v_mov_b32_e32 v78, v72
	v_mov_b32_e32 v76, v81
	v_add_u32_e32 v72, 0x80, v146
	v_ashrrev_i32_e32 v73, 31, v72
	v_mad_i64_i32 v[80:81], s[44:45], v88, s68, v[118:119]
	v_lshl_add_u64 v[88:89], v[72:73], 2, s[10:11]
	v_lshl_add_u64 v[80:81], v[80:81], 0, v[120:121]
	v_mov_b32_e32 v82, v178
	v_pk_mul_f32 v[74:75], v[74:75], v[82:83] op_sel_hi:[1,0]
	v_pk_mul_f32 v[66:67], v[66:67], v[82:83] op_sel_hi:[1,0]
	v_pk_mul_f32 v[70:71], v[70:71], v[82:83] op_sel_hi:[1,0]
	v_pk_mul_f32 v[68:69], v[68:69], v[82:83] op_sel_hi:[1,0]
	v_pk_mul_f32 v[84:85], v[84:85], v[82:83] op_sel_hi:[1,0]
	v_pk_mul_f32 v[86:87], v[86:87], v[82:83] op_sel_hi:[1,0]
	v_pk_mul_f32 v[78:79], v[78:79], v[82:83] op_sel_hi:[1,0]
	v_pk_mul_f32 v[76:77], v[76:77], v[82:83] op_sel_hi:[1,0]
	v_mul_f32_e32 v83, 0xbfb8aa3b, v75
	v_mul_f32_e32 v90, 0xbfb8aa3b, v67
	v_mul_f32_e32 v91, 0xbfb8aa3b, v71
	v_mul_f32_e32 v94, 0xbfb8aa3b, v69
	v_mul_f32_e32 v73, 0xbfb8aa3b, v85
	v_mul_f32_e32 v82, 0xbfb8aa3b, v87
	v_mul_f32_e32 v92, 0xbfb8aa3b, v79
	v_mul_f32_e32 v93, 0xbfb8aa3b, v77
	v_exp_f32_e32 v83, v83
	v_exp_f32_e32 v90, v90
	v_exp_f32_e32 v91, v91
	v_exp_f32_e32 v94, v94
	v_exp_f32_e32 v73, v73
	v_exp_f32_e32 v82, v82
	v_exp_f32_e32 v92, v92
	v_exp_f32_e32 v93, v93
	v_add_f32_e32 v83, 1.0, v83
	v_add_f32_e32 v90, 1.0, v90
	v_add_f32_e32 v91, 1.0, v91
	v_add_f32_e32 v94, 1.0, v94
	v_add_f32_e32 v73, 1.0, v73
	v_add_f32_e32 v82, 1.0, v82
	v_add_f32_e32 v92, 1.0, v92
	v_add_f32_e32 v93, 1.0, v93
	v_rcp_f32_e32 v83, v83
	v_rcp_f32_e32 v90, v90
	v_rcp_f32_e32 v91, v91
	v_rcp_f32_e32 v94, v94
	v_rcp_f32_e32 v73, v73
	v_rcp_f32_e32 v82, v82
	v_rcp_f32_e32 v92, v92
	v_rcp_f32_e32 v93, v93
	v_mul_f32_e32 v75, v75, v83
	v_mul_f32_e32 v67, v67, v90
	v_mul_f32_e32 v71, v71, v91
	v_mul_f32_e32 v69, v69, v94
	v_mul_f32_e32 v73, v85, v73
	v_mul_f32_e32 v82, v87, v82
	v_mul_f32_e32 v79, v79, v92
	v_mul_f32_e32 v77, v77, v93
	v_mul_f32_e32 v74, v74, v75
	v_mul_f32_e32 v75, v66, v67
	v_mul_f32_e32 v67, v70, v71
	v_mul_f32_e32 v69, v68, v69
	v_mul_f32_e32 v73, v84, v73
	v_mul_f32_e32 v82, v86, v82
	v_mul_f32_e32 v70, v78, v79
	v_mul_f32_e32 v71, v76, v77
; __device__ __forceinline__ u32x4 pack8f(const f32x4 a, const f32x4 b) { u32x4 w; w.x = cvt_pk_bf16(a[0], a[1]); w.y = cvt_pk_bf16(a[2], a[3]); w.z = cvt_pk_bf16(b[0], b[1]); w.w = cvt_pk_bf16(b[2], b[3]); return w; }
;     __device__ __forceinline__ void operator()(const f32x4 (&acc)[2][2][4][2], const Unit& u, int wr, int wc, int fr, int fq) const {
;     ...
;                 const int row = u.pm * BM + ai * HALF + wr * 64 + m * 16 + fr; const float rr = rs[row];
;                 f32x4 r0, r1;
; #pragma unroll
;                 for (int e = 0; e < 4; ++e) {
;                     const float g0 = acc[ai][0][m][0][e] * rr, g1 = acc[ai][0][m][1][e] * rr;
;                     r0[e] = g0 * __builtin_amdgcn_rcpf(1.f + __builtin_amdgcn_exp2f(-1.4426950408889634f * g0)) * (acc[ai][1][m][0][e] * rr);
;                     r1[e] = g1 * __builtin_amdgcn_rcpf(1.f + __builtin_amdgcn_exp2f(-1.4426950408889634f * g1)) * (acc[ai][1][m][1][e] * rr);
;                 }
;                 *(u32x4*)(O + (size_t)row * ldc + col0) = pack8f(r0, r1);
	v_cvt_pk_bf16_f32 v66, v73, v74
	v_cvt_pk_bf16_f32 v67, v67, v71
	v_cvt_pk_bf16_f32 v68, v82, v75
	v_cvt_pk_bf16_f32 v69, v70, v69
	global_store_dwordx4 v[80:81], v[66:69], off
	s_nop 1
	v_mov_b32_e32 v70, v54
	v_mov_b32_e32 v69, v58
	v_mov_b32_e32 v71, v50
	v_mov_b32_e32 v58, v63
	v_mov_b32_e32 v50, v55
	v_mov_b32_e32 v54, v64
	v_mov_b32_e32 v55, v60
	v_mov_b32_e32 v63, v52
	v_mov_b32_e32 v52, v57
	v_mov_b32_e32 v68, v62
	v_mov_b32_e32 v62, v56
	v_mov_b32_e32 v60, v65
	v_add_u32_e32 v56, 0x90, v146
	v_ashrrev_i32_e32 v57, 31, v56
	v_mad_i64_i32 v[64:65], s[44:45], v72, s68, v[118:119]
	v_lshl_add_u64 v[72:73], v[56:57], 2, s[10:11]
	v_lshl_add_u64 v[64:65], v[64:65], 0, v[120:121]
	v_mov_b32_e32 v66, v180
	v_pk_mul_f32 v[58:59], v[58:59], v[66:67] op_sel_hi:[1,0]
	v_pk_mul_f32 v[50:51], v[50:51], v[66:67] op_sel_hi:[1,0]
	v_pk_mul_f32 v[54:55], v[54:55], v[66:67] op_sel_hi:[1,0]
	v_pk_mul_f32 v[52:53], v[52:53], v[66:67] op_sel_hi:[1,0]
	v_pk_mul_f32 v[68:69], v[68:69], v[66:67] op_sel_hi:[1,0]
	v_pk_mul_f32 v[70:71], v[70:71], v[66:67] op_sel_hi:[1,0]
	v_pk_mul_f32 v[62:63], v[62:63], v[66:67] op_sel_hi:[1,0]
	v_pk_mul_f32 v[60:61], v[60:61], v[66:67] op_sel_hi:[1,0]
	v_mul_f32_e32 v67, 0xbfb8aa3b, v59
	v_mul_f32_e32 v74, 0xbfb8aa3b, v51
	v_mul_f32_e32 v75, 0xbfb8aa3b, v55
	v_mul_f32_e32 v78, 0xbfb8aa3b, v53
	v_mul_f32_e32 v57, 0xbfb8aa3b, v69
	v_mul_f32_e32 v66, 0xbfb8aa3b, v71
	v_mul_f32_e32 v76, 0xbfb8aa3b, v63
	v_mul_f32_e32 v77, 0xbfb8aa3b, v61
	v_exp_f32_e32 v67, v67
	v_exp_f32_e32 v74, v74
	v_exp_f32_e32 v75, v75
	v_exp_f32_e32 v78, v78
	v_exp_f32_e32 v57, v57
	v_exp_f32_e32 v66, v66
	v_exp_f32_e32 v76, v76
	v_exp_f32_e32 v77, v77
	v_add_f32_e32 v67, 1.0, v67
	v_add_f32_e32 v74, 1.0, v74
	v_add_f32_e32 v75, 1.0, v75
	v_add_f32_e32 v78, 1.0, v78
	v_add_f32_e32 v57, 1.0, v57
	v_add_f32_e32 v66, 1.0, v66
	v_add_f32_e32 v76, 1.0, v76
	v_add_f32_e32 v77, 1.0, v77
	v_rcp_f32_e32 v67, v67
	v_rcp_f32_e32 v74, v74
	v_rcp_f32_e32 v75, v75
	v_rcp_f32_e32 v78, v78
	v_rcp_f32_e32 v57, v57
	v_rcp_f32_e32 v66, v66
	v_rcp_f32_e32 v76, v76
	v_rcp_f32_e32 v77, v77
	v_mul_f32_e32 v59, v59, v67
	v_mul_f32_e32 v51, v51, v74
	v_mul_f32_e32 v55, v55, v75
	v_mul_f32_e32 v53, v53, v78
	v_mul_f32_e32 v57, v69, v57
	v_mul_f32_e32 v66, v71, v66
	v_mul_f32_e32 v63, v63, v76
	v_mul_f32_e32 v61, v61, v77
	v_mul_f32_e32 v58, v58, v59
	v_mul_f32_e32 v59, v50, v51
	v_mul_f32_e32 v51, v54, v55
	v_mul_f32_e32 v53, v52, v53
	v_mul_f32_e32 v57, v68, v57
	v_mul_f32_e32 v66, v70, v66
	v_mul_f32_e32 v54, v62, v63
	v_mul_f32_e32 v55, v60, v61
	v_cvt_pk_bf16_f32 v50, v57, v58
	v_cvt_pk_bf16_f32 v51, v51, v55
	v_cvt_pk_bf16_f32 v52, v66, v59
	v_cvt_pk_bf16_f32 v53, v54, v53
	global_store_dwordx4 v[64:65], v[50:53], off
	s_nop 1
	v_mov_b32_e32 v54, v38
	v_mov_b32_e32 v53, v42
	v_mov_b32_e32 v55, v34
	v_mov_b32_e32 v42, v47
	v_mov_b32_e32 v34, v39
	v_mov_b32_e32 v38, v48
	v_mov_b32_e32 v39, v44
	v_mov_b32_e32 v47, v36
	v_mov_b32_e32 v36, v41
	v_mov_b32_e32 v52, v46
	v_mov_b32_e32 v46, v40
	v_mov_b32_e32 v44, v49
	v_add_u32_e32 v40, 0xa0, v146
	v_ashrrev_i32_e32 v41, 31, v40
	v_mad_i64_i32 v[48:49], s[44:45], v56, s68, v[118:119]
	v_lshl_add_u64 v[56:57], v[40:41], 2, s[10:11]
	v_lshl_add_u64 v[48:49], v[48:49], 0, v[120:121]
	v_mov_b32_e32 v50, v182
	v_pk_mul_f32 v[42:43], v[42:43], v[50:51] op_sel_hi:[1,0]
	v_pk_mul_f32 v[34:35], v[34:35], v[50:51] op_sel_hi:[1,0]
	v_pk_mul_f32 v[38:39], v[38:39], v[50:51] op_sel_hi:[1,0]
	v_pk_mul_f32 v[36:37], v[36:37], v[50:51] op_sel_hi:[1,0]
	v_pk_mul_f32 v[52:53], v[52:53], v[50:51] op_sel_hi:[1,0]
	v_pk_mul_f32 v[54:55], v[54:55], v[50:51] op_sel_hi:[1,0]
	v_pk_mul_f32 v[46:47], v[46:47], v[50:51] op_sel_hi:[1,0]
	v_pk_mul_f32 v[44:45], v[44:45], v[50:51] op_sel_hi:[1,0]
	v_mul_f32_e32 v51, 0xbfb8aa3b, v43
	v_mul_f32_e32 v58, 0xbfb8aa3b, v35
	v_mul_f32_e32 v59, 0xbfb8aa3b, v39
	v_mul_f32_e32 v62, 0xbfb8aa3b, v37
	v_mul_f32_e32 v41, 0xbfb8aa3b, v53
	v_mul_f32_e32 v50, 0xbfb8aa3b, v55
	v_mul_f32_e32 v60, 0xbfb8aa3b, v47
	v_mul_f32_e32 v61, 0xbfb8aa3b, v45
	v_exp_f32_e32 v51, v51
	v_exp_f32_e32 v58, v58
	v_exp_f32_e32 v59, v59
	v_exp_f32_e32 v62, v62
	v_exp_f32_e32 v41, v41
	v_exp_f32_e32 v50, v50
	v_exp_f32_e32 v60, v60
	v_exp_f32_e32 v61, v61
	v_add_f32_e32 v51, 1.0, v51
	v_add_f32_e32 v58, 1.0, v58
	v_add_f32_e32 v59, 1.0, v59
	v_add_f32_e32 v62, 1.0, v62
	v_add_f32_e32 v41, 1.0, v41
	v_add_f32_e32 v50, 1.0, v50
	v_add_f32_e32 v60, 1.0, v60
	v_add_f32_e32 v61, 1.0, v61
	v_rcp_f32_e32 v51, v51
	v_rcp_f32_e32 v58, v58
	v_rcp_f32_e32 v59, v59
	v_rcp_f32_e32 v62, v62
	v_rcp_f32_e32 v41, v41
	v_rcp_f32_e32 v50, v50
	v_rcp_f32_e32 v60, v60
	v_rcp_f32_e32 v61, v61
	v_mul_f32_e32 v43, v43, v51
	v_mul_f32_e32 v35, v35, v58
	v_mul_f32_e32 v39, v39, v59
	v_mul_f32_e32 v37, v37, v62
	v_mul_f32_e32 v41, v53, v41
	v_mul_f32_e32 v50, v55, v50
	v_mul_f32_e32 v47, v47, v60
	v_mul_f32_e32 v45, v45, v61
	v_mul_f32_e32 v42, v42, v43
	v_mul_f32_e32 v43, v34, v35
	v_mul_f32_e32 v35, v38, v39
	v_mul_f32_e32 v37, v36, v37
	v_mul_f32_e32 v41, v52, v41
	v_mul_f32_e32 v50, v54, v50
	v_mul_f32_e32 v38, v46, v47
	v_mul_f32_e32 v39, v44, v45
	v_cvt_pk_bf16_f32 v34, v41, v42
	v_cvt_pk_bf16_f32 v35, v35, v39
; __device__ __forceinline__ u32x4 pack8f(const f32x4 a, const f32x4 b) { u32x4 w; w.x = cvt_pk_bf16(a[0], a[1]); w.y = cvt_pk_bf16(a[2], a[3]); w.z = cvt_pk_bf16(b[0], b[1]); w.w = cvt_pk_bf16(b[2], b[3]); return w; }
; #define PG8_BAR __builtin_amdgcn_s_barrier()
;     __device__ __forceinline__ void operator()(const f32x4 (&acc)[2][2][4][2], const Unit& u, int wr, int wc, int fr, int fq) const {
;     ...
;                 const int row = u.pm * BM + ai * HALF + wr * 64 + m * 16 + fr; const float rr = rs[row];
;                 f32x4 r0, r1;
; #pragma unroll
;                 for (int e = 0; e < 4; ++e) {
;                     const float g0 = acc[ai][0][m][0][e] * rr, g1 = acc[ai][0][m][1][e] * rr;
;                     r0[e] = g0 * __builtin_amdgcn_rcpf(1.f + __builtin_amdgcn_exp2f(-1.4426950408889634f * g0)) * (acc[ai][1][m][0][e] * rr);
;                     r1[e] = g1 * __builtin_amdgcn_rcpf(1.f + __builtin_amdgcn_exp2f(-1.4426950408889634f * g1)) * (acc[ai][1][m][1][e] * rr);
;                 }
;                 *(u32x4*)(O + (size_t)row * ldc + col0) = pack8f(r0, r1);
; template <class Epi, class Sched, bool ALIGN_EPI = false, bool SP2 = false>
; __device__ __forceinline__ void gemm_phase(PG8_LAS unsigned char* lds, const Gemm g, const Sched& S, const Epi& E) {
;     ...
;         if (!has_next) break;
; #pragma unroll
;         for (int a = 0; a < 2; ++a)
; #pragma unroll
;             for (int b = 0; b < 2; ++b)
; #pragma unroll
;                 for (int m = 0; m < 4; ++m)
; #pragma unroll
;                     for (int n = 0; n < 2; ++n) acc[a][b][m][n] = (f32x4){0.f, 0.f, 0.f, 0.f};
;         cur = nxt; cA = nA; cB = nB; ++ui;
;         if constexpr (ALIGN_EPI) { if (wr == 1) PG8_BAR; }
	v_cvt_pk_bf16_f32 v36, v50, v43
	v_cvt_pk_bf16_f32 v37, v38, v37
	global_store_dwordx4 v[48:49], v[34:37], off
	s_nop 1
	v_mov_b32_e32 v38, v22
	v_mov_b32_e32 v37, v26
	v_mov_b32_e32 v39, v18
	v_mov_b32_e32 v26, v31
	v_mov_b32_e32 v18, v23
	v_mov_b32_e32 v22, v32
	v_mov_b32_e32 v23, v28
	v_mov_b32_e32 v31, v20
	v_mov_b32_e32 v20, v25
	v_mov_b32_e32 v36, v30
	v_mov_b32_e32 v30, v24
	v_mov_b32_e32 v28, v33
	v_add_u32_e32 v24, 0xb0, v146
	v_ashrrev_i32_e32 v25, 31, v24
	v_mad_i64_i32 v[32:33], s[44:45], v40, s68, v[118:119]
	v_lshl_add_u64 v[40:41], v[24:25], 2, s[10:11]
	v_lshl_add_u64 v[32:33], v[32:33], 0, v[120:121]
	v_mov_b32_e32 v34, v184
	v_pk_mul_f32 v[26:27], v[26:27], v[34:35] op_sel_hi:[1,0]
	v_pk_mul_f32 v[18:19], v[18:19], v[34:35] op_sel_hi:[1,0]
	v_pk_mul_f32 v[22:23], v[22:23], v[34:35] op_sel_hi:[1,0]
	v_pk_mul_f32 v[20:21], v[20:21], v[34:35] op_sel_hi:[1,0]
	v_pk_mul_f32 v[36:37], v[36:37], v[34:35] op_sel_hi:[1,0]
	v_pk_mul_f32 v[38:39], v[38:39], v[34:35] op_sel_hi:[1,0]
	v_pk_mul_f32 v[30:31], v[30:31], v[34:35] op_sel_hi:[1,0]
	v_pk_mul_f32 v[28:29], v[28:29], v[34:35] op_sel_hi:[1,0]
	v_mul_f32_e32 v35, 0xbfb8aa3b, v27
	v_mul_f32_e32 v42, 0xbfb8aa3b, v19
	v_mul_f32_e32 v43, 0xbfb8aa3b, v23
	v_mul_f32_e32 v46, 0xbfb8aa3b, v21
	v_mul_f32_e32 v25, 0xbfb8aa3b, v37
	v_mul_f32_e32 v34, 0xbfb8aa3b, v39
	v_mul_f32_e32 v44, 0xbfb8aa3b, v31
	v_mul_f32_e32 v45, 0xbfb8aa3b, v29
	v_exp_f32_e32 v35, v35
	v_exp_f32_e32 v42, v42
	v_exp_f32_e32 v43, v43
	v_exp_f32_e32 v46, v46
	v_exp_f32_e32 v25, v25
	v_exp_f32_e32 v34, v34
	v_exp_f32_e32 v44, v44
	v_exp_f32_e32 v45, v45
	v_add_f32_e32 v35, 1.0, v35
	v_add_f32_e32 v42, 1.0, v42
	v_add_f32_e32 v43, 1.0, v43
	v_add_f32_e32 v46, 1.0, v46
	v_add_f32_e32 v25, 1.0, v25
	v_add_f32_e32 v34, 1.0, v34
	v_add_f32_e32 v44, 1.0, v44
	v_add_f32_e32 v45, 1.0, v45
	v_rcp_f32_e32 v35, v35
	v_rcp_f32_e32 v42, v42
	v_rcp_f32_e32 v43, v43
	v_rcp_f32_e32 v46, v46
	v_rcp_f32_e32 v25, v25
	v_rcp_f32_e32 v34, v34
	v_rcp_f32_e32 v44, v44
	v_rcp_f32_e32 v45, v45
	v_mul_f32_e32 v27, v27, v35
	v_mul_f32_e32 v19, v19, v42
	v_mul_f32_e32 v23, v23, v43
	v_mul_f32_e32 v21, v21, v46
	v_mul_f32_e32 v25, v37, v25
	v_mul_f32_e32 v34, v39, v34
	v_mul_f32_e32 v31, v31, v44
	v_mul_f32_e32 v29, v29, v45
	v_mul_f32_e32 v26, v26, v27
	v_mul_f32_e32 v27, v18, v19
	v_mul_f32_e32 v19, v22, v23
	v_mul_f32_e32 v21, v20, v21
	v_mul_f32_e32 v25, v36, v25
	v_mul_f32_e32 v34, v38, v34
	v_mul_f32_e32 v22, v30, v31
	v_mul_f32_e32 v23, v28, v29
	v_cvt_pk_bf16_f32 v18, v25, v26
	v_cvt_pk_bf16_f32 v19, v19, v23
	v_cvt_pk_bf16_f32 v20, v34, v27
	v_cvt_pk_bf16_f32 v21, v22, v21
	global_store_dwordx4 v[32:33], v[18:21], off
	s_nop 1
	v_mov_b32_e32 v22, v2
	v_mov_b32_e32 v20, v14
	v_mov_b32_e32 v21, v10
	v_mov_b32_e32 v23, v6
	v_mov_b32_e32 v10, v15
	v_mov_b32_e32 v6, v3
	v_mov_b32_e32 v2, v16
	v_mov_b32_e32 v3, v12
	v_mov_b32_e32 v14, v4
	v_mov_b32_e32 v15, v8
	v_mov_b32_e32 v8, v5
	v_mad_i64_i32 v[4:5], s[44:45], v24, s68, v[118:119]
	v_mov_b32_e32 v12, v17
	v_lshl_add_u64 v[16:17], v[4:5], 0, v[120:121]
	v_mov_b32_e32 v18, v186
	v_pk_mul_f32 v[4:5], v[20:21], v[18:19] op_sel_hi:[1,0]
	v_pk_mul_f32 v[20:21], v[22:23], v[18:19] op_sel_hi:[1,0]
	v_pk_mul_f32 v[2:3], v[2:3], v[18:19] op_sel_hi:[1,0]
	v_pk_mul_f32 v[10:11], v[10:11], v[18:19] op_sel_hi:[1,0]
	v_pk_mul_f32 v[6:7], v[6:7], v[18:19] op_sel_hi:[1,0]
	v_pk_mul_f32 v[14:15], v[14:15], v[18:19] op_sel_hi:[1,0]
	v_pk_mul_f32 v[12:13], v[12:13], v[18:19] op_sel_hi:[1,0]
	v_pk_mul_f32 v[8:9], v[8:9], v[18:19] op_sel_hi:[1,0]
	v_mul_f32_e32 v18, 0xbfb8aa3b, v5
	v_mul_f32_e32 v19, 0xbfb8aa3b, v21
	v_mul_f32_e32 v24, 0xbfb8aa3b, v3
	v_mul_f32_e32 v22, 0xbfb8aa3b, v11
	v_mul_f32_e32 v23, 0xbfb8aa3b, v7
	v_mul_f32_e32 v25, 0xbfb8aa3b, v15
	v_mul_f32_e32 v26, 0xbfb8aa3b, v13
	v_mul_f32_e32 v27, 0xbfb8aa3b, v9
	v_exp_f32_e32 v18, v18
	v_exp_f32_e32 v19, v19
	v_exp_f32_e32 v24, v24
	v_exp_f32_e32 v22, v22
	v_exp_f32_e32 v23, v23
	v_exp_f32_e32 v25, v25
	v_exp_f32_e32 v26, v26
	v_exp_f32_e32 v27, v27
	v_add_f32_e32 v18, 1.0, v18
	v_add_f32_e32 v19, 1.0, v19
	v_add_f32_e32 v24, 1.0, v24
	v_add_f32_e32 v22, 1.0, v22
	v_add_f32_e32 v23, 1.0, v23
	v_add_f32_e32 v25, 1.0, v25
	v_add_f32_e32 v26, 1.0, v26
	v_add_f32_e32 v27, 1.0, v27
	v_rcp_f32_e32 v18, v18
	v_rcp_f32_e32 v19, v19
	v_rcp_f32_e32 v24, v24
	v_rcp_f32_e32 v22, v22
	v_rcp_f32_e32 v23, v23
	v_rcp_f32_e32 v25, v25
	v_rcp_f32_e32 v26, v26
	v_rcp_f32_e32 v27, v27
	v_mul_f32_e32 v5, v5, v18
	v_mul_f32_e32 v18, v21, v19
	v_mul_f32_e32 v3, v3, v24
	v_mul_f32_e32 v11, v11, v22
	v_mul_f32_e32 v7, v7, v23
	v_mul_f32_e32 v15, v15, v25
	v_mul_f32_e32 v13, v13, v26
	v_mul_f32_e32 v9, v9, v27
	v_mul_f32_e32 v4, v4, v5
	v_mul_f32_e32 v5, v20, v18
	v_mul_f32_e32 v3, v2, v3
	v_mul_f32_e32 v10, v10, v11
	v_mul_f32_e32 v6, v6, v7
	v_mul_f32_e32 v7, v14, v15
	v_mul_f32_e32 v11, v12, v13
	v_mul_f32_e32 v8, v8, v9
	v_cvt_pk_bf16_f32 v2, v4, v10
	v_cvt_pk_bf16_f32 v3, v3, v11
	v_cvt_pk_bf16_f32 v4, v5, v6
	v_cvt_pk_bf16_f32 v5, v7, v8
	global_store_dwordx4 v[16:17], v[2:5], off
	s_cbranch_vccnz .LBB0_877
	s_andn2_b64 vcc, exec, s[6:7]
	s_cbranch_vccnz .LBB0_876
	s_barrier
	s_branch .LBB0_876

; __device__ __forceinline__ KP kargs() { KP q = (KP)__builtin_amdgcn_kernarg_segment_ptr(); asm volatile("" : "+s"(q)); return q; }
; __global__ void __launch_bounds__(512, 2) fwd_mega(Params P_by_kernarg) {
;     ...
;         const KP KA = kargs(); unsigned char* const ws = KA->ws;
;         const f32x4* gp = (const f32x4*)KA->in[22] + lane;
;         for (int row = gw; row < MX; row += 2 * NGW) {
;             const int rB = (row + NGW < MX) ? row + NGW : row; const bool hasB = row + NGW < MX;
;             const float sA = ssq2[(size_t)row * 64 + lane], sB = ssq2[(size_t)rB * 64 + lane];
.LBB0_1070:
.LBB0_1071:
	s_cmp_lt_i32 s33, 9
	s_cselect_b64 s[4:5], -1, 0
	s_and_b64 s[2:3], s[4:5], s[2:3]
	s_andn2_b64 vcc, exec, s[2:3]
	s_cbranch_vccnz .LBB0_1077
	s_cmpk_gt_i32 s18, 0x1fff
	s_cbranch_scc1 .LBB0_1077
	s_waitcnt vmcnt(0)
	v_mbcnt_lo_u32_b32 v8, -1, 0
	v_mbcnt_hi_u32_b32 v8, -1, v8
	v_and_b32_e32 v9, 64, v8
	v_add_u32_e32 v9, 64, v9
	v_xor_b32_e32 v10, 1, v8
	v_cmp_lt_i32_e32 vcc, v10, v9
	s_load_dwordx2 s[2:3], s[0:1], 0xb0
	s_load_dwordx4 s[4:7], s[0:1], 0xb8
	v_cndmask_b32_e32 v10, v8, v10, vcc
	v_lshlrev_b32_e32 v115, 2, v10
	v_xor_b32_e32 v10, 2, v8
	v_cmp_lt_i32_e32 vcc, v10, v9
	v_lshlrev_b32_e32 v34, 4, v196
	v_mov_b32_e32 v35, 0
	v_cndmask_b32_e32 v10, v8, v10, vcc
	v_lshlrev_b32_e32 v154, 2, v10
	v_xor_b32_e32 v10, 4, v8
	v_cmp_lt_i32_e32 vcc, v10, v9
	s_waitcnt lgkmcnt(0)
	v_lshl_add_u64 v[0:1], s[2:3], 0, v[34:35]
	s_mov_b64 s[2:3], 0x1000
	v_cndmask_b32_e32 v10, v8, v10, vcc
	v_lshlrev_b32_e32 v155, 2, v10
	v_xor_b32_e32 v10, 8, v8
	v_cmp_lt_i32_e32 vcc, v10, v9
	v_lshlrev_b32_e32 v38, 3, v196
	v_mov_b32_e32 v39, v35
	v_cndmask_b32_e32 v10, v8, v10, vcc
	v_lshlrev_b32_e32 v156, 2, v10
	v_xor_b32_e32 v10, 16, v8
	v_cmp_lt_i32_e32 vcc, v10, v9
	v_lshl_add_u64 v[6:7], s[6:7], 0, v[38:39]
	s_mov_b64 s[0:1], 0x27e00000
	v_cndmask_b32_e32 v10, v8, v10, vcc
	v_lshlrev_b32_e32 v157, 2, v10
	v_xor_b32_e32 v10, 32, v8
	v_cmp_lt_i32_e32 vcc, v10, v9
	v_lshl_add_u64 v[4:5], v[6:7], 0, s[0:1]
	s_mov_b64 s[0:1], 0x30200000
	v_cndmask_b32_e32 v8, v8, v10, vcc
	v_lshl_add_u64 v[10:11], v[0:1], 0, s[2:3]
	s_mov_b64 s[2:3], 0x1400
	v_lshl_add_u64 v[12:13], v[0:1], 0, s[2:3]
	s_mov_b64 s[2:3], 0x1800
	v_lshl_add_u64 v[14:15], v[0:1], 0, s[2:3]
	s_mov_b64 s[2:3], 0x1c00
	v_lshl_add_u64 v[16:17], v[0:1], 0, s[2:3]
	s_mov_b64 s[2:3], 0x2000
	v_lshl_add_u64 v[18:19], v[0:1], 0, s[2:3]
	s_mov_b64 s[2:3], 0x2400
	s_ashr_i32 s19, s18, 31
	v_lshl_add_u64 v[6:7], v[6:7], 0, s[0:1]
	s_lshl_b32 s0, s22, 4
	v_lshl_add_u64 v[20:21], v[0:1], 0, s[2:3]
	s_mov_b64 s[2:3], 0x2800
	s_lshl_b64 s[10:11], s[18:19], 14
	v_lshlrev_b32_e32 v158, 2, v8
	v_lshl_add_u64 v[8:9], s[4:5], 0, v[34:35]
	v_lshl_add_u64 v[22:23], v[0:1], 0, s[2:3]
	s_mov_b64 s[2:3], 0x2c00
	s_add_u32 s4, s4, s10
	v_lshl_add_u64 v[24:25], v[0:1], 0, s[2:3]
	s_mov_b64 s[2:3], 0x3000
	s_addc_u32 s5, s5, s11
	v_lshlrev_b32_e32 v36, 2, v196
	v_mov_b32_e32 v37, v35
	v_lshl_add_u64 v[26:27], v[0:1], 0, s[2:3]
	s_mov_b64 s[2:3], 0x3400
	v_lshl_add_u64 v[34:35], s[4:5], 0, v[34:35]
	s_lshl_b64 s[4:5], s[18:19], 8
	v_lshl_add_u64 v[2:3], s[6:7], 0, v[36:37]
	s_mov_b64 s[8:9], 0x18a00000
	v_lshl_add_u64 v[28:29], v[0:1], 0, s[2:3]
	s_mov_b64 s[2:3], 0x3800
	v_or_b32_e32 v36, s4, v36
	v_mov_b32_e32 v37, s5
	v_lshl_add_u64 v[2:3], v[2:3], 0, s[8:9]
	v_lshl_add_u64 v[30:31], v[0:1], 0, s[2:3]
	s_mov_b64 s[2:3], 0x3c00
	s_ashr_i32 s1, s0, 31
	v_lshl_add_u64 v[36:37], v[36:37], 0, s[8:9]
	s_lshl_b64 s[8:9], s[18:19], 13
	v_lshl_add_u64 v[32:33], v[0:1], 0, s[2:3]
	v_lshl_add_u64 v[34:35], v[34:35], 0, s[2:3]
	s_lshl_b64 s[2:3], s[0:1], 14
	s_lshl_b64 s[4:5], s[0:1], 8
	v_or_b32_e32 v38, s8, v38
	v_mov_b32_e32 v39, s9
	s_lshl_b64 s[8:9], s[0:1], 13
	s_movk_i32 s1, 0x2000
	s_mov_b32 s12, 0x27e00000
	s_mov_b32 s13, 0x30200000
	s_mov_b32 s14, 0x27e01000
	s_mov_b32 s15, 0x30201000
	s_movk_i32 s16, 0x1000
	v_mov_b32_e32 v159, 0x358637bd
	s_mov_b32 s17, 0x800000
	s_movk_i32 s19, 0xd000
	s_movk_i32 s21, 0xe000
	s_movk_i32 s22, 0xf000
	s_movk_i32 s23, 0x3000
	global_load_dwordx4 v[188:191], v[0:1], off
	global_load_dwordx4 v[192:195], v[0:1], off offset:1024
	global_load_dwordx4 v[200:203], v[0:1], off offset:2048
	global_load_dwordx4 v[204:207], v[0:1], off offset:3072
	global_load_dwordx4 v[208:211], v[10:11], off
	global_load_dwordx4 v[212:215], v[12:13], off
	global_load_dwordx4 v[216:219], v[14:15], off
	global_load_dwordx4 v[220:223], v[16:17], off
	global_load_dwordx4 v[224:227], v[18:19], off
	global_load_dwordx4 v[228:231], v[20:21], off
	global_load_dwordx4 v[232:235], v[22:23], off
	global_load_dwordx4 v[236:239], v[24:25], off
	global_load_dwordx4 v[240:243], v[26:27], off
	global_load_dwordx4 v[244:247], v[28:29], off
	global_load_dwordx4 v[248:251], v[30:31], off
	global_load_dwordx4 v[252:255], v[32:33], off
	s_branch .LBB0_1075

; __global__ void __launch_bounds__(512, 2) fwd_mega(Params P_by_kernarg) {
;     ...
;         for (int row = gw; row < MX; row += 2 * NGW) {
;             const int rB = (row + NGW < MX) ? row + NGW : row; const bool hasB = row + NGW < MX;
;             const float sA = ssq2[(size_t)row * 64 + lane], sB = ssq2[(size_t)rB * 64 + lane];
;             u32x2 fa[16], ha[16], fb[16], hb[16];
;             { const u32x2* f4 = (const u32x2*)(Mixed + (size_t)row * DM) + lane; const u32x2* h8 = (const u32x2*)(H1b + (size_t)row * DM) + lane;
; #pragma unroll
;               for (int j = 0; j < 16; ++j) { fa[j] = f4[64 * j]; ha[j] = h8[64 * j]; } }
;             { const u32x2* f4 = (const u32x2*)(Mixed + (size_t)rB * DM) + lane; const u32x2* h8 = (const u32x2*)(H1b + (size_t)rB * DM) + lane;
; #pragma unroll
;               for (int j = 0; j < 16; ++j) { fb[j] = f4[64 * j]; hb[j] = h8[64 * j]; } }
.LBB0_1075:
	v_lshl_add_u64 v[40:41], s[6:7], 0, v[36:37]
	global_load_dword v48, v[40:41], off
	global_load_dwordx4 v[162:165], v[0:1], off
	v_lshl_add_u64 v[40:41], s[6:7], 0, v[38:39]
	v_add_co_u32_e32 v42, vcc, s12, v40
	s_add_i32 s24, s20, s18
	s_nop 0
	v_addc_co_u32_e32 v43, vcc, 0, v41, vcc
	v_add_co_u32_e32 v44, vcc, s14, v40
	s_cmpk_lt_i32 s24, 0x2000
	s_nop 0
	v_addc_co_u32_e32 v45, vcc, 0, v41, vcc
	v_add_co_u32_e32 v46, vcc, s13, v40
	s_cselect_b32 s10, s24, s18
	s_nop 0
	v_addc_co_u32_e32 v47, vcc, 0, v41, vcc
	v_add_co_u32_e32 v40, vcc, s15, v40
	s_ashr_i32 s11, s10, 31
	s_nop 0
	v_addc_co_u32_e32 v41, vcc, 0, v41, vcc
	global_load_dwordx2 v[166:167], v[44:45], off offset:-4096
	global_load_dwordx2 v[168:169], v[40:41], off offset:-4096
	global_load_dwordx2 v[170:171], v[42:43], off offset:1536
	global_load_dwordx2 v[150:151], v[42:43], off offset:2048
	global_load_dwordx2 v[146:147], v[42:43], off offset:2560
	global_load_dwordx2 v[142:143], v[42:43], off offset:3072
	global_load_dwordx2 v[172:173], v[46:47], off offset:512
	global_load_dwordx2 v[174:175], v[46:47], off offset:1024
	global_load_dwordx2 v[176:177], v[46:47], off offset:1536
	global_load_dwordx2 v[138:139], v[42:43], off offset:3584
	global_load_dwordx2 v[152:153], v[46:47], off offset:2048
	global_load_dwordx2 v[148:149], v[46:47], off offset:2560
	global_load_dwordx2 v[144:145], v[46:47], off offset:3072
	global_load_dwordx2 v[140:141], v[46:47], off offset:3584
	global_load_dwordx2 v[134:135], v[44:45], off
	global_load_dwordx2 v[130:131], v[44:45], off offset:512
	global_load_dwordx2 v[128:129], v[44:45], off offset:1024
	global_load_dwordx2 v[126:127], v[40:41], off offset:1024
	global_load_dwordx2 v[122:123], v[40:41], off offset:1536
	global_load_dwordx2 v[118:119], v[40:41], off offset:2048
	global_load_dwordx2 v[112:113], v[40:41], off offset:2560
	global_load_dwordx2 v[124:125], v[44:45], off offset:1536
	global_load_dwordx2 v[120:121], v[44:45], off offset:2048
	global_load_dwordx2 v[116:117], v[44:45], off offset:2560
	global_load_dwordx2 v[108:109], v[44:45], off offset:3072
	global_load_dwordx2 v[136:137], v[40:41], off
	global_load_dwordx2 v[132:133], v[40:41], off offset:512
	global_load_dwordx2 v[106:107], v[44:45], off offset:3584
	global_load_dwordx2 v[110:111], v[40:41], off offset:3072
	global_load_dwordx2 v[104:105], v[40:41], off offset:3584
	s_lshl_b64 s[26:27], s[10:11], 8
	s_lshl_b64 s[28:29], s[10:11], 13
	v_lshl_add_u64 v[40:41], v[2:3], 0, s[26:27]
	v_lshl_add_u64 v[44:45], v[4:5], 0, s[28:29]
	v_lshl_add_u64 v[46:47], v[6:7], 0, s[28:29]
	global_load_dword v160, v[40:41], off
	global_load_dwordx2 v[178:179], v[42:43], off offset:512
	global_load_dwordx2 v[180:181], v[42:43], off offset:1024
	global_load_dwordx2 v[102:103], v[44:45], off
	global_load_dwordx2 v[96:97], v[44:45], off offset:512
	global_load_dwordx2 v[92:93], v[44:45], off offset:1024
	global_load_dwordx2 v[88:89], v[44:45], off offset:1536
	global_load_dwordx2 v[100:101], v[46:47], off
	global_load_dwordx2 v[98:99], v[46:47], off offset:512
	global_load_dwordx2 v[94:95], v[46:47], off offset:1024
	global_load_dwordx2 v[90:91], v[46:47], off offset:1536
	global_load_dwordx2 v[84:85], v[44:45], off offset:2048
	global_load_dwordx2 v[80:81], v[44:45], off offset:2560
	global_load_dwordx2 v[76:77], v[44:45], off offset:3072
	global_load_dwordx2 v[72:73], v[44:45], off offset:3584
	global_load_dwordx2 v[86:87], v[46:47], off offset:2048
	global_load_dwordx2 v[82:83], v[46:47], off offset:2560
	global_load_dwordx2 v[78:79], v[46:47], off offset:3072
	global_load_dwordx2 v[74:75], v[46:47], off offset:3584
	v_add_co_u32_e32 v40, vcc, s16, v44
	s_cmpk_gt_i32 s24, 0x1fff
	s_nop 0
	v_addc_co_u32_e32 v41, vcc, 0, v45, vcc
	global_load_dwordx2 v[68:69], v[40:41], off
	global_load_dwordx2 v[64:65], v[40:41], off offset:512
	global_load_dwordx2 v[60:61], v[40:41], off offset:1024
	global_load_dwordx2 v[56:57], v[40:41], off offset:1536
	s_waitcnt vmcnt(52)
	v_lshlrev_b32_e32 v182, 16, v166
	v_and_b32_e32 v183, 0xffff0000, v166
	v_lshlrev_b32_e32 v166, 16, v167
	v_and_b32_e32 v167, 0xffff0000, v167
	s_waitcnt vmcnt(51)
	v_lshlrev_b32_e32 v184, 16, v168
	v_and_b32_e32 v185, 0xffff0000, v168
	v_lshlrev_b32_e32 v168, 16, v169
	ds_bpermute_b32 v42, v115, v48
	v_and_b32_e32 v169, 0xffff0000, v169
	s_waitcnt lgkmcnt(0)
	v_add_f32_e32 v44, v48, v42
	ds_bpermute_b32 v45, v154, v44
	v_add_co_u32_e32 v42, vcc, s16, v46
	s_waitcnt lgkmcnt(0)
	v_add_f32_e32 v44, v44, v45
	ds_bpermute_b32 v45, v155, v44
	v_addc_co_u32_e32 v43, vcc, 0, v47, vcc
	global_load_dwordx2 v[70:71], v[42:43], off
	global_load_dwordx2 v[66:67], v[42:43], off offset:512
	global_load_dwordx2 v[62:63], v[42:43], off offset:1024
	global_load_dwordx2 v[58:59], v[42:43], off offset:1536
	s_waitcnt lgkmcnt(0)
	v_add_f32_e32 v44, v44, v45
	ds_bpermute_b32 v45, v156, v44
	s_waitcnt lgkmcnt(0)
	v_add_f32_e32 v46, v44, v45
	ds_bpermute_b32 v47, v157, v46
	global_load_dwordx2 v[52:53], v[40:41], off offset:2048
	global_load_dwordx2 v[48:49], v[40:41], off offset:2560
	global_load_dwordx2 v[44:45], v[40:41], off offset:3072
	s_nop 0
	global_load_dwordx2 v[40:41], v[40:41], off offset:3584
	s_waitcnt lgkmcnt(0)
	v_add_f32_e32 v114, v46, v47
	ds_bpermute_b32 v161, v158, v114
	global_load_dwordx2 v[54:55], v[42:43], off offset:2048
	global_load_dwordx2 v[50:51], v[42:43], off offset:2560
	global_load_dwordx2 v[46:47], v[42:43], off offset:3072
	s_nop 0
	global_load_dwordx2 v[42:43], v[42:43], off offset:3584
	s_waitcnt lgkmcnt(0)
; __global__ void __launch_bounds__(512, 2) fwd_mega(Params P_by_kernarg) {
;     ...
;             P8_ROW(row, fa, ha, sA);
	v_add_f32_e32 v114, v114, v161
	v_fmamk_f32 v114, v114, 0x39800000, v159
	v_mul_f32_e32 v161, 0x4b800000, v114
	v_cmp_gt_f32_e32 vcc, s17, v114
	s_nop 1
	v_cndmask_b32_e32 v114, v114, v161, vcc
	v_rsq_f32_e32 v114, v114
	s_nop 0
	v_mul_f32_e32 v161, 0x45800000, v114
	v_cndmask_b32_e32 v114, v114, v161, vcc
	v_pk_mul_f32 v[166:167], v[114:115], v[166:167] op_sel_hi:[0,1]
	v_pk_mul_f32 v[182:183], v[114:115], v[182:183] op_sel_hi:[0,1]
	v_pk_fma_f32 v[164:165], v[164:165], v[166:167], v[168:169]
	v_add_co_u32_e32 v166, vcc, s19, v34
	v_pk_fma_f32 v[162:163], v[162:163], v[182:183], v[184:185]
	s_nop 0
	v_addc_co_u32_e32 v167, vcc, -1, v35, vcc
	s_waitcnt vmcnt(0)
	global_store_dwordx4 v[166:167], v[162:165], off offset:-3072 nt
	s_nop 1
	v_lshlrev_b32_e32 v182, 16, v178
	v_and_b32_e32 v183, 0xffff0000, v178
	v_lshlrev_b32_e32 v178, 16, v179
	v_and_b32_e32 v179, 0xffff0000, v179
	v_lshlrev_b32_e32 v168, 16, v172
	v_and_b32_e32 v169, 0xffff0000, v172
	v_lshlrev_b32_e32 v172, 16, v173
	v_and_b32_e32 v173, 0xffff0000, v173
	v_pk_mul_f32 v[178:179], v[114:115], v[178:179] op_sel_hi:[0,1]
	v_pk_mul_f32 v[182:183], v[114:115], v[182:183] op_sel_hi:[0,1]
	v_pk_fma_f32 v[162:163], v[192:193], v[182:183], v[168:169]
	v_pk_fma_f32 v[164:165], v[194:195], v[178:179], v[172:173]
	global_store_dwordx4 v[166:167], v[162:165], off offset:-2048 nt
	s_nop 1
	v_lshlrev_b32_e32 v168, 16, v174
	v_and_b32_e32 v169, 0xffff0000, v174
	v_lshlrev_b32_e32 v172, 16, v175
	v_and_b32_e32 v173, 0xffff0000, v175
	v_lshlrev_b32_e32 v174, 16, v180
	v_and_b32_e32 v175, 0xffff0000, v180
	v_lshlrev_b32_e32 v178, 16, v181
	v_and_b32_e32 v179, 0xffff0000, v181
	v_pk_mul_f32 v[178:179], v[114:115], v[178:179] op_sel_hi:[0,1]
	v_pk_mul_f32 v[174:175], v[114:115], v[174:175] op_sel_hi:[0,1]
	v_pk_fma_f32 v[162:163], v[200:201], v[174:175], v[168:169]
	v_pk_fma_f32 v[164:165], v[202:203], v[178:179], v[172:173]
	global_store_dwordx4 v[166:167], v[162:165], off offset:-1024 nt
	s_nop 1
	v_lshlrev_b32_e32 v168, 16, v170
	v_and_b32_e32 v169, 0xffff0000, v170
	v_lshlrev_b32_e32 v170, 16, v171
	v_and_b32_e32 v171, 0xffff0000, v171
	v_add_co_u32_e32 v166, vcc, s21, v34
	v_lshlrev_b32_e32 v172, 16, v176
	v_and_b32_e32 v173, 0xffff0000, v176
	v_lshlrev_b32_e32 v174, 16, v177
	v_and_b32_e32 v175, 0xffff0000, v177
	v_pk_mul_f32 v[170:171], v[114:115], v[170:171] op_sel_hi:[0,1]
	v_pk_mul_f32 v[168:169], v[114:115], v[168:169] op_sel_hi:[0,1]
	v_addc_co_u32_e32 v167, vcc, -1, v35, vcc
	v_pk_fma_f32 v[162:163], v[204:205], v[168:169], v[172:173]
	v_pk_fma_f32 v[164:165], v[206:207], v[170:171], v[174:175]
	global_store_dwordx4 v[166:167], v[162:165], off offset:-4096 nt
	s_nop 1
	v_lshlrev_b32_e32 v168, 16, v150
	v_and_b32_e32 v169, 0xffff0000, v150
	v_lshlrev_b32_e32 v150, 16, v151
	v_and_b32_e32 v151, 0xffff0000, v151
	v_lshlrev_b32_e32 v170, 16, v152
	v_and_b32_e32 v171, 0xffff0000, v152
	v_lshlrev_b32_e32 v152, 16, v153
	v_and_b32_e32 v153, 0xffff0000, v153
	v_pk_mul_f32 v[172:173], v[114:115], v[150:151] op_sel_hi:[0,1]
	v_pk_mul_f32 v[150:151], v[114:115], v[168:169] op_sel_hi:[0,1]
	v_pk_fma_f32 v[150:151], v[208:209], v[150:151], v[170:171]
	v_pk_fma_f32 v[152:153], v[210:211], v[172:173], v[152:153]
	global_store_dwordx4 v[166:167], v[150:153], off offset:-3072 nt
	s_nop 1
	v_lshlrev_b32_e32 v162, 16, v146
	v_and_b32_e32 v163, 0xffff0000, v146
	v_lshlrev_b32_e32 v146, 16, v147
	v_and_b32_e32 v147, 0xffff0000, v147
	v_lshlrev_b32_e32 v164, 16, v148
	v_and_b32_e32 v165, 0xffff0000, v148
	v_lshlrev_b32_e32 v148, 16, v149
	v_and_b32_e32 v149, 0xffff0000, v149
	v_pk_mul_f32 v[168:169], v[114:115], v[146:147] op_sel_hi:[0,1]
	v_pk_mul_f32 v[146:147], v[114:115], v[162:163] op_sel_hi:[0,1]
	v_pk_fma_f32 v[146:147], v[212:213], v[146:147], v[164:165]
	v_pk_fma_f32 v[148:149], v[214:215], v[168:169], v[148:149]
	global_store_dwordx4 v[166:167], v[146:149], off offset:-2048 nt
	s_nop 1
	v_lshlrev_b32_e32 v150, 16, v142
	v_and_b32_e32 v151, 0xffff0000, v142
	v_lshlrev_b32_e32 v142, 16, v143
	v_and_b32_e32 v143, 0xffff0000, v143
	v_lshlrev_b32_e32 v152, 16, v144
	v_and_b32_e32 v153, 0xffff0000, v144
	v_lshlrev_b32_e32 v144, 16, v145
	v_and_b32_e32 v145, 0xffff0000, v145
	v_pk_mul_f32 v[162:163], v[114:115], v[142:143] op_sel_hi:[0,1]
	v_pk_mul_f32 v[142:143], v[114:115], v[150:151] op_sel_hi:[0,1]
	v_pk_fma_f32 v[142:143], v[216:217], v[142:143], v[152:153]
	v_pk_fma_f32 v[144:145], v[218:219], v[162:163], v[144:145]
	global_store_dwordx4 v[166:167], v[142:145], off offset:-1024 nt
	s_nop 1
	v_lshlrev_b32_e32 v146, 16, v138
	v_and_b32_e32 v147, 0xffff0000, v138
	v_lshlrev_b32_e32 v138, 16, v139
	v_and_b32_e32 v139, 0xffff0000, v139
	v_lshlrev_b32_e32 v148, 16, v140
	v_and_b32_e32 v149, 0xffff0000, v140
	v_lshlrev_b32_e32 v140, 16, v141
	v_and_b32_e32 v141, 0xffff0000, v141
	v_pk_mul_f32 v[150:151], v[114:115], v[138:139] op_sel_hi:[0,1]
	v_pk_mul_f32 v[138:139], v[114:115], v[146:147] op_sel_hi:[0,1]
	v_lshlrev_b32_e32 v146, 16, v136
	v_and_b32_e32 v147, 0xffff0000, v136
	v_lshlrev_b32_e32 v136, 16, v137
	v_and_b32_e32 v137, 0xffff0000, v137
	v_pk_fma_f32 v[138:139], v[220:221], v[138:139], v[148:149]
	v_pk_fma_f32 v[140:141], v[222:223], v[150:151], v[140:141]
	global_store_dwordx4 v[166:167], v[138:141], off nt
	s_nop 1
	v_lshlrev_b32_e32 v144, 16, v134
	v_and_b32_e32 v145, 0xffff0000, v134
	v_lshlrev_b32_e32 v134, 16, v135
	v_and_b32_e32 v135, 0xffff0000, v135
	v_add_co_u32_e32 v142, vcc, s22, v34
	v_pk_mul_f32 v[148:149], v[114:115], v[134:135] op_sel_hi:[0,1]
	v_pk_mul_f32 v[134:135], v[114:115], v[144:145] op_sel_hi:[0,1]
	v_addc_co_u32_e32 v143, vcc, -1, v35, vcc
; __global__ void __launch_bounds__(512, 2) fwd_mega(Params P_by_kernarg) {
;     ...
;             P8_ROW(row, fa, ha, sA);
;             if (hasB) P8_ROW(rB, fb, hb, sB);
	v_pk_fma_f32 v[134:135], v[224:225], v[134:135], v[146:147]
	v_pk_fma_f32 v[136:137], v[226:227], v[148:149], v[136:137]
	global_store_dwordx4 v[142:143], v[134:137], off offset:-3072 nt
	s_nop 1
	v_lshlrev_b32_e32 v138, 16, v130
	v_and_b32_e32 v139, 0xffff0000, v130
	v_lshlrev_b32_e32 v130, 16, v131
	v_and_b32_e32 v131, 0xffff0000, v131
	v_lshlrev_b32_e32 v140, 16, v132
	v_and_b32_e32 v141, 0xffff0000, v132
	v_lshlrev_b32_e32 v132, 16, v133
	v_and_b32_e32 v133, 0xffff0000, v133
	v_pk_mul_f32 v[144:145], v[114:115], v[130:131] op_sel_hi:[0,1]
	v_pk_mul_f32 v[130:131], v[114:115], v[138:139] op_sel_hi:[0,1]
	v_lshlrev_b32_e32 v138, 16, v127
	v_and_b32_e32 v139, 0xffff0000, v127
	v_pk_fma_f32 v[130:131], v[228:229], v[130:131], v[140:141]
	v_pk_fma_f32 v[132:133], v[230:231], v[144:145], v[132:133]
	global_store_dwordx4 v[142:143], v[130:133], off offset:-2048 nt
	s_nop 1
	v_lshlrev_b32_e32 v134, 16, v128
	v_and_b32_e32 v135, 0xffff0000, v128
	v_lshlrev_b32_e32 v128, 16, v129
	v_and_b32_e32 v129, 0xffff0000, v129
	v_lshlrev_b32_e32 v136, 16, v126
	v_and_b32_e32 v137, 0xffff0000, v126
	v_pk_mul_f32 v[128:129], v[114:115], v[128:129] op_sel_hi:[0,1]
	v_pk_mul_f32 v[126:127], v[114:115], v[134:135] op_sel_hi:[0,1]
	v_lshlrev_b32_e32 v134, 16, v123
	v_and_b32_e32 v135, 0xffff0000, v123
	v_pk_fma_f32 v[126:127], v[232:233], v[126:127], v[136:137]
	v_pk_fma_f32 v[128:129], v[234:235], v[128:129], v[138:139]
	global_store_dwordx4 v[142:143], v[126:129], off offset:-1024 nt
	s_nop 1
	v_lshlrev_b32_e32 v130, 16, v124
	v_and_b32_e32 v131, 0xffff0000, v124
	v_lshlrev_b32_e32 v124, 16, v125
	v_and_b32_e32 v125, 0xffff0000, v125
	v_lshlrev_b32_e32 v132, 16, v122
	v_and_b32_e32 v133, 0xffff0000, v122
	v_pk_mul_f32 v[124:125], v[114:115], v[124:125] op_sel_hi:[0,1]
	v_pk_mul_f32 v[122:123], v[114:115], v[130:131] op_sel_hi:[0,1]
	v_lshlrev_b32_e32 v130, 16, v119
	v_and_b32_e32 v131, 0xffff0000, v119
	v_pk_fma_f32 v[122:123], v[236:237], v[122:123], v[132:133]
	v_pk_fma_f32 v[124:125], v[238:239], v[124:125], v[134:135]
	global_store_dwordx4 v[34:35], v[122:125], off offset:-4096 nt
	s_nop 1
	v_lshlrev_b32_e32 v126, 16, v120
	v_and_b32_e32 v127, 0xffff0000, v120
	v_lshlrev_b32_e32 v120, 16, v121
	v_and_b32_e32 v121, 0xffff0000, v121
	v_lshlrev_b32_e32 v128, 16, v118
	v_and_b32_e32 v129, 0xffff0000, v118
	v_pk_mul_f32 v[120:121], v[114:115], v[120:121] op_sel_hi:[0,1]
	v_pk_mul_f32 v[118:119], v[114:115], v[126:127] op_sel_hi:[0,1]
	v_pk_fma_f32 v[118:119], v[240:241], v[118:119], v[128:129]
	v_pk_fma_f32 v[120:121], v[242:243], v[120:121], v[130:131]
	global_store_dwordx4 v[34:35], v[118:121], off offset:-3072 nt
	s_nop 1
	v_lshlrev_b32_e32 v122, 16, v116
	v_and_b32_e32 v123, 0xffff0000, v116
	v_lshlrev_b32_e32 v116, 16, v117
	v_and_b32_e32 v117, 0xffff0000, v117
	v_lshlrev_b32_e32 v124, 16, v112
	v_and_b32_e32 v125, 0xffff0000, v112
	v_lshlrev_b32_e32 v112, 16, v113
	v_and_b32_e32 v113, 0xffff0000, v113
	v_pk_mul_f32 v[126:127], v[114:115], v[116:117] op_sel_hi:[0,1]
	v_pk_mul_f32 v[116:117], v[114:115], v[122:123] op_sel_hi:[0,1]
	v_pk_fma_f32 v[116:117], v[244:245], v[116:117], v[124:125]
	v_pk_fma_f32 v[118:119], v[246:247], v[126:127], v[112:113]
	global_store_dwordx4 v[34:35], v[116:119], off offset:-2048 nt
	s_nop 1
	v_lshlrev_b32_e32 v112, 16, v108
	v_and_b32_e32 v113, 0xffff0000, v108
	v_lshlrev_b32_e32 v108, 16, v109
	v_and_b32_e32 v109, 0xffff0000, v109
	v_lshlrev_b32_e32 v120, 16, v110
	v_and_b32_e32 v121, 0xffff0000, v110
	v_lshlrev_b32_e32 v110, 16, v111
	v_and_b32_e32 v111, 0xffff0000, v111
	v_pk_mul_f32 v[122:123], v[114:115], v[108:109] op_sel_hi:[0,1]
	v_pk_mul_f32 v[108:109], v[114:115], v[112:113] op_sel_hi:[0,1]
	v_lshlrev_b32_e32 v112, 16, v106
	v_and_b32_e32 v113, 0xffff0000, v106
	v_lshlrev_b32_e32 v106, 16, v107
	v_and_b32_e32 v107, 0xffff0000, v107
	v_pk_mul_f32 v[106:107], v[114:115], v[106:107] op_sel_hi:[0,1]
	v_pk_fma_f32 v[108:109], v[248:249], v[108:109], v[120:121]
	v_pk_fma_f32 v[110:111], v[250:251], v[122:123], v[110:111]
	global_store_dwordx4 v[34:35], v[108:111], off offset:-1024 nt
	s_nop 1
	v_lshlrev_b32_e32 v116, 16, v104
	v_and_b32_e32 v117, 0xffff0000, v104
	v_lshlrev_b32_e32 v118, 16, v105
	v_and_b32_e32 v119, 0xffff0000, v105
	v_pk_mul_f32 v[104:105], v[114:115], v[112:113] op_sel_hi:[0,1]
	v_pk_fma_f32 v[104:105], v[252:253], v[104:105], v[116:117]
	v_pk_fma_f32 v[106:107], v[254:255], v[106:107], v[118:119]
	global_store_dwordx4 v[34:35], v[104:107], off nt
	s_cbranch_scc1 .LBB0_1074
; __global__ void __launch_bounds__(512, 2) fwd_mega(Params P_by_kernarg) {
;     ...
;             P8_ROW(row, fa, ha, sA);
;             if (hasB) P8_ROW(rB, fb, hb, sB);
	s_nop 1
	ds_bpermute_b32 v108, v115, v160
	v_lshlrev_b32_e32 v112, 16, v100
	v_and_b32_e32 v113, 0xffff0000, v100
	v_lshlrev_b32_e32 v116, 16, v101
	v_and_b32_e32 v117, 0xffff0000, v101
	s_waitcnt lgkmcnt(0)
	v_add_f32_e32 v108, v160, v108
	ds_bpermute_b32 v109, v154, v108
	s_lshl_b64 s[10:11], s[10:11], 12
	s_waitcnt lgkmcnt(0)
	v_add_f32_e32 v108, v108, v109
	ds_bpermute_b32 v109, v155, v108
	s_waitcnt lgkmcnt(0)
	v_add_f32_e32 v108, v108, v109
	ds_bpermute_b32 v109, v156, v108
	s_waitcnt lgkmcnt(0)
	v_add_f32_e32 v110, v108, v109
	ds_bpermute_b32 v111, v157, v110
	v_lshlrev_b32_e32 v108, 16, v102
	v_and_b32_e32 v109, 0xffff0000, v102
	s_waitcnt lgkmcnt(0)
	v_add_f32_e32 v102, v110, v111
	ds_bpermute_b32 v114, v158, v102
	v_lshlrev_b32_e32 v110, 16, v103
	v_and_b32_e32 v111, 0xffff0000, v103
	s_waitcnt lgkmcnt(0)
	v_add_f32_e32 v100, v102, v114
	v_fmamk_f32 v100, v100, 0x39800000, v159
	v_mul_f32_e32 v102, 0x4b800000, v100
	v_cmp_gt_f32_e32 vcc, s17, v100
	s_nop 1
	v_cndmask_b32_e32 v100, v100, v102, vcc
	v_rsq_f32_e32 v100, v100
	v_lshl_add_u64 v[102:103], s[10:11], 2, v[8:9]
	v_mul_f32_e32 v101, 0x45800000, v100
	v_cndmask_b32_e32 v100, v100, v101, vcc
	v_pk_mul_f32 v[108:109], v[100:101], v[108:109] op_sel_hi:[0,1]
	v_pk_mul_f32 v[110:111], v[100:101], v[110:111] op_sel_hi:[0,1]
	v_pk_fma_f32 v[106:107], v[190:191], v[110:111], v[116:117]
	v_pk_fma_f32 v[104:105], v[188:189], v[108:109], v[112:113]
	global_store_dwordx4 v[102:103], v[104:107], off nt
	s_nop 1
	v_lshlrev_b32_e32 v108, 16, v96
	v_and_b32_e32 v109, 0xffff0000, v96
	v_lshlrev_b32_e32 v96, 16, v97
	v_and_b32_e32 v97, 0xffff0000, v97
	v_lshlrev_b32_e32 v110, 16, v98
	v_and_b32_e32 v111, 0xffff0000, v98
	v_lshlrev_b32_e32 v98, 16, v99
	v_and_b32_e32 v99, 0xffff0000, v99
	v_pk_mul_f32 v[112:113], v[100:101], v[96:97] op_sel_hi:[0,1]
	v_pk_mul_f32 v[96:97], v[100:101], v[108:109] op_sel_hi:[0,1]
	v_pk_fma_f32 v[96:97], v[192:193], v[96:97], v[110:111]
	v_pk_fma_f32 v[98:99], v[194:195], v[112:113], v[98:99]
	global_store_dwordx4 v[102:103], v[96:99], off offset:1024 nt
	s_nop 1
	v_lshlrev_b32_e32 v104, 16, v92
	v_and_b32_e32 v105, 0xffff0000, v92
	v_lshlrev_b32_e32 v92, 16, v93
	v_and_b32_e32 v93, 0xffff0000, v93
	v_lshlrev_b32_e32 v106, 16, v94
	v_and_b32_e32 v107, 0xffff0000, v94
	v_lshlrev_b32_e32 v94, 16, v95
	v_and_b32_e32 v95, 0xffff0000, v95
	v_pk_mul_f32 v[108:109], v[100:101], v[92:93] op_sel_hi:[0,1]
	v_pk_mul_f32 v[92:93], v[100:101], v[104:105] op_sel_hi:[0,1]
	v_pk_fma_f32 v[92:93], v[200:201], v[92:93], v[106:107]
	v_pk_fma_f32 v[94:95], v[202:203], v[108:109], v[94:95]
	global_store_dwordx4 v[102:103], v[92:95], off offset:2048 nt
	s_nop 1
	v_lshlrev_b32_e32 v96, 16, v88
	v_and_b32_e32 v97, 0xffff0000, v88
	v_lshlrev_b32_e32 v88, 16, v89
	v_and_b32_e32 v89, 0xffff0000, v89
	v_lshlrev_b32_e32 v98, 16, v90
	v_and_b32_e32 v99, 0xffff0000, v90
	v_lshlrev_b32_e32 v90, 16, v91
	v_and_b32_e32 v91, 0xffff0000, v91
	v_pk_mul_f32 v[104:105], v[100:101], v[88:89] op_sel_hi:[0,1]
	v_pk_mul_f32 v[88:89], v[100:101], v[96:97] op_sel_hi:[0,1]
	v_lshlrev_b32_e32 v96, 16, v86
	v_and_b32_e32 v97, 0xffff0000, v86
	v_pk_fma_f32 v[88:89], v[204:205], v[88:89], v[98:99]
	v_pk_fma_f32 v[90:91], v[206:207], v[104:105], v[90:91]
	global_store_dwordx4 v[102:103], v[88:91], off offset:3072 nt
	s_nop 1
	v_lshlrev_b32_e32 v92, 16, v84
	v_and_b32_e32 v93, 0xffff0000, v84
	v_lshlrev_b32_e32 v94, 16, v85
	v_and_b32_e32 v95, 0xffff0000, v85
	v_lshlrev_b32_e32 v98, 16, v87
	v_and_b32_e32 v99, 0xffff0000, v87
	v_add_co_u32_e32 v84, vcc, s1, v102
	v_pk_mul_f32 v[94:95], v[100:101], v[94:95] op_sel_hi:[0,1]
	v_pk_mul_f32 v[86:87], v[100:101], v[92:93] op_sel_hi:[0,1]
	v_addc_co_u32_e32 v85, vcc, 0, v103, vcc
	v_lshlrev_b32_e32 v92, 16, v82
	v_and_b32_e32 v93, 0xffff0000, v82
	v_lshlrev_b32_e32 v82, 16, v83
	v_and_b32_e32 v83, 0xffff0000, v83
	v_pk_fma_f32 v[86:87], v[208:209], v[86:87], v[96:97]
	v_pk_fma_f32 v[88:89], v[210:211], v[94:95], v[98:99]
	global_store_dwordx4 v[84:85], v[86:89], off offset:-4096 nt
	s_nop 1
	v_lshlrev_b32_e32 v90, 16, v80
	v_and_b32_e32 v91, 0xffff0000, v80
	v_lshlrev_b32_e32 v80, 16, v81
	v_and_b32_e32 v81, 0xffff0000, v81
	v_add_co_u32_e32 v94, vcc, s16, v102
	v_pk_mul_f32 v[96:97], v[100:101], v[80:81] op_sel_hi:[0,1]
	v_pk_mul_f32 v[80:81], v[100:101], v[90:91] op_sel_hi:[0,1]
	v_addc_co_u32_e32 v95, vcc, 0, v103, vcc
	v_pk_fma_f32 v[80:81], v[212:213], v[80:81], v[92:93]
	v_pk_fma_f32 v[82:83], v[214:215], v[96:97], v[82:83]
	global_store_dwordx4 v[94:95], v[80:83], off offset:1024 nt
	s_nop 1
	v_lshlrev_b32_e32 v86, 16, v76
	v_and_b32_e32 v87, 0xffff0000, v76
	v_lshlrev_b32_e32 v76, 16, v77
	v_and_b32_e32 v77, 0xffff0000, v77
	v_lshlrev_b32_e32 v88, 16, v78
	v_and_b32_e32 v89, 0xffff0000, v78
	v_lshlrev_b32_e32 v78, 16, v79
	v_and_b32_e32 v79, 0xffff0000, v79
	v_pk_mul_f32 v[90:91], v[100:101], v[76:77] op_sel_hi:[0,1]
	v_pk_mul_f32 v[76:77], v[100:101], v[86:87] op_sel_hi:[0,1]
	v_pk_fma_f32 v[76:77], v[216:217], v[76:77], v[88:89]
	v_pk_fma_f32 v[78:79], v[218:219], v[90:91], v[78:79]
	global_store_dwordx4 v[94:95], v[76:79], off offset:2048 nt
	s_nop 1
	v_lshlrev_b32_e32 v80, 16, v72
	v_and_b32_e32 v81, 0xffff0000, v72
; __global__ void __launch_bounds__(512, 2) fwd_mega(Params P_by_kernarg) {
;     ...
;             P8_ROW(row, fa, ha, sA);
;             if (hasB) P8_ROW(rB, fb, hb, sB);
;     ...
;         }
	v_lshlrev_b32_e32 v72, 16, v73
	v_and_b32_e32 v73, 0xffff0000, v73
	v_lshlrev_b32_e32 v82, 16, v74
	v_and_b32_e32 v83, 0xffff0000, v74
	v_lshlrev_b32_e32 v74, 16, v75
	v_and_b32_e32 v75, 0xffff0000, v75
	v_pk_mul_f32 v[86:87], v[100:101], v[72:73] op_sel_hi:[0,1]
	v_pk_mul_f32 v[72:73], v[100:101], v[80:81] op_sel_hi:[0,1]
	v_pk_fma_f32 v[72:73], v[220:221], v[72:73], v[82:83]
	v_pk_fma_f32 v[74:75], v[222:223], v[86:87], v[74:75]
	global_store_dwordx4 v[94:95], v[72:75], off offset:3072 nt
	s_nop 1
	v_lshlrev_b32_e32 v76, 16, v68
	v_and_b32_e32 v77, 0xffff0000, v68
	v_lshlrev_b32_e32 v68, 16, v69
	v_and_b32_e32 v69, 0xffff0000, v69
	v_lshlrev_b32_e32 v78, 16, v70
	v_and_b32_e32 v79, 0xffff0000, v70
	v_lshlrev_b32_e32 v70, 16, v71
	v_and_b32_e32 v71, 0xffff0000, v71
	v_pk_mul_f32 v[80:81], v[100:101], v[68:69] op_sel_hi:[0,1]
	v_pk_mul_f32 v[68:69], v[100:101], v[76:77] op_sel_hi:[0,1]
	v_pk_fma_f32 v[68:69], v[224:225], v[68:69], v[78:79]
	v_pk_fma_f32 v[70:71], v[226:227], v[80:81], v[70:71]
	global_store_dwordx4 v[84:85], v[68:71], off nt
	s_nop 1
	v_lshlrev_b32_e32 v72, 16, v64
	v_and_b32_e32 v73, 0xffff0000, v64
	v_lshlrev_b32_e32 v64, 16, v65
	v_and_b32_e32 v65, 0xffff0000, v65
	v_lshlrev_b32_e32 v74, 16, v66
	v_and_b32_e32 v75, 0xffff0000, v66
	v_lshlrev_b32_e32 v66, 16, v67
	v_and_b32_e32 v67, 0xffff0000, v67
	v_pk_mul_f32 v[76:77], v[100:101], v[64:65] op_sel_hi:[0,1]
	v_pk_mul_f32 v[64:65], v[100:101], v[72:73] op_sel_hi:[0,1]
	v_pk_fma_f32 v[64:65], v[228:229], v[64:65], v[74:75]
	v_pk_fma_f32 v[66:67], v[230:231], v[76:77], v[66:67]
	global_store_dwordx4 v[84:85], v[64:67], off offset:1024 nt
	s_nop 1
	v_lshlrev_b32_e32 v68, 16, v60
	v_and_b32_e32 v69, 0xffff0000, v60
	v_lshlrev_b32_e32 v60, 16, v61
	v_and_b32_e32 v61, 0xffff0000, v61
	v_lshlrev_b32_e32 v70, 16, v62
	v_and_b32_e32 v71, 0xffff0000, v62
	v_lshlrev_b32_e32 v62, 16, v63
	v_and_b32_e32 v63, 0xffff0000, v63
	v_pk_mul_f32 v[72:73], v[100:101], v[60:61] op_sel_hi:[0,1]
	v_pk_mul_f32 v[60:61], v[100:101], v[68:69] op_sel_hi:[0,1]
	v_pk_fma_f32 v[60:61], v[232:233], v[60:61], v[70:71]
	v_pk_fma_f32 v[62:63], v[234:235], v[72:73], v[62:63]
	global_store_dwordx4 v[84:85], v[60:63], off offset:2048 nt
	s_nop 1
	v_lshlrev_b32_e32 v64, 16, v56
	v_and_b32_e32 v65, 0xffff0000, v56
	v_lshlrev_b32_e32 v56, 16, v57
	v_and_b32_e32 v57, 0xffff0000, v57
	v_lshlrev_b32_e32 v66, 16, v58
	v_and_b32_e32 v67, 0xffff0000, v58
	v_lshlrev_b32_e32 v58, 16, v59
	v_and_b32_e32 v59, 0xffff0000, v59
	v_pk_mul_f32 v[68:69], v[100:101], v[56:57] op_sel_hi:[0,1]
	v_pk_mul_f32 v[56:57], v[100:101], v[64:65] op_sel_hi:[0,1]
	v_add_co_u32_e32 v64, vcc, s23, v102
	v_pk_fma_f32 v[56:57], v[236:237], v[56:57], v[66:67]
	v_pk_fma_f32 v[58:59], v[238:239], v[68:69], v[58:59]
	global_store_dwordx4 v[84:85], v[56:59], off offset:3072 nt
	s_nop 1
	v_lshlrev_b32_e32 v60, 16, v52
	v_and_b32_e32 v61, 0xffff0000, v52
	v_lshlrev_b32_e32 v52, 16, v53
	v_and_b32_e32 v53, 0xffff0000, v53
	v_lshlrev_b32_e32 v62, 16, v54
	v_and_b32_e32 v63, 0xffff0000, v54
	v_lshlrev_b32_e32 v54, 16, v55
	v_and_b32_e32 v55, 0xffff0000, v55
	v_pk_mul_f32 v[66:67], v[100:101], v[52:53] op_sel_hi:[0,1]
	v_pk_mul_f32 v[52:53], v[100:101], v[60:61] op_sel_hi:[0,1]
	v_addc_co_u32_e32 v65, vcc, 0, v103, vcc
	v_pk_fma_f32 v[52:53], v[240:241], v[52:53], v[62:63]
	v_pk_fma_f32 v[54:55], v[242:243], v[66:67], v[54:55]
	global_store_dwordx4 v[64:65], v[52:55], off nt
	s_nop 1
	v_lshlrev_b32_e32 v56, 16, v48
	v_and_b32_e32 v57, 0xffff0000, v48
	v_lshlrev_b32_e32 v48, 16, v49
	v_and_b32_e32 v49, 0xffff0000, v49
	v_lshlrev_b32_e32 v58, 16, v50
	v_and_b32_e32 v59, 0xffff0000, v50
	v_lshlrev_b32_e32 v50, 16, v51
	v_and_b32_e32 v51, 0xffff0000, v51
	v_pk_mul_f32 v[60:61], v[100:101], v[48:49] op_sel_hi:[0,1]
	v_pk_mul_f32 v[48:49], v[100:101], v[56:57] op_sel_hi:[0,1]
	v_pk_fma_f32 v[48:49], v[244:245], v[48:49], v[58:59]
	v_pk_fma_f32 v[50:51], v[246:247], v[60:61], v[50:51]
	global_store_dwordx4 v[64:65], v[48:51], off offset:1024 nt
	s_nop 1
	v_lshlrev_b32_e32 v52, 16, v44
	v_and_b32_e32 v53, 0xffff0000, v44
	v_lshlrev_b32_e32 v44, 16, v45
	v_and_b32_e32 v45, 0xffff0000, v45
	v_lshlrev_b32_e32 v54, 16, v46
	v_and_b32_e32 v55, 0xffff0000, v46
	v_lshlrev_b32_e32 v46, 16, v47
	v_and_b32_e32 v47, 0xffff0000, v47
	v_pk_mul_f32 v[56:57], v[100:101], v[44:45] op_sel_hi:[0,1]
	v_pk_mul_f32 v[44:45], v[100:101], v[52:53] op_sel_hi:[0,1]
	v_pk_fma_f32 v[44:45], v[248:249], v[44:45], v[54:55]
	v_pk_fma_f32 v[46:47], v[250:251], v[56:57], v[46:47]
	global_store_dwordx4 v[64:65], v[44:47], off offset:2048 nt
	s_nop 1
	v_lshlrev_b32_e32 v48, 16, v40
	v_and_b32_e32 v49, 0xffff0000, v40
	v_lshlrev_b32_e32 v40, 16, v41
	v_and_b32_e32 v41, 0xffff0000, v41
	v_lshlrev_b32_e32 v50, 16, v42
	v_and_b32_e32 v51, 0xffff0000, v42
	v_lshlrev_b32_e32 v42, 16, v43
	v_and_b32_e32 v43, 0xffff0000, v43
	v_pk_mul_f32 v[52:53], v[100:101], v[40:41] op_sel_hi:[0,1]
	v_pk_mul_f32 v[40:41], v[100:101], v[48:49] op_sel_hi:[0,1]
	v_pk_fma_f32 v[40:41], v[252:253], v[40:41], v[50:51]
	v_pk_fma_f32 v[42:43], v[254:255], v[52:53], v[42:43]
	global_store_dwordx4 v[64:65], v[40:43], off offset:3072 nt
	s_branch .LBB0_1074
